# attention tile loop: three of the four second-chain Q fragments also prefetched before the tile barrier (only one LDS read left between QK chains 1 and 2)
# speedup vs baseline: 1.0062x; 1.0062x over previous
; #define LAS __attribute__((address_space(3)))
; template <bool SHIFT> DI void phase_attn2(const Params& p, const Grp& G, int layer, LAS unsigned char* lds, int tid, int wave, int lane, int vcu, bool dry) {
;     ...
;         const int qb = u % NQB, bh = u / NQB, h = bh & 3, b = bh >> 2; const size_t seq0 = (size_t)b * G.S; const size_t qrow0 = seq0 + (size_t)qb * 256;
;         bf16x8 qf[2][4];
;         int lq = (int)__builtin_amdgcn_mbcnt_hi(~0u, __builtin_amdgcn_mbcnt_lo(~0u, 0u)); asm volatile("" : "+v"(lq));
; #pragma unroll
;         for (int rbq = 0; rbq < 2; ++rbq) { const bf16_t* qp = mix + (qrow0 + 64 * qg + 32 * rbq + (lq & 31)) * MIXW + h * 128 + c * 64 + 8 * (lq >> 5);
; #pragma unroll
;           for (int d0 = 0; d0 < 4; ++d0) qf[rbq][d0] = *(const bf16x8*)(qp + 16 * d0); }
;         LAS unsigned char* Qs = lds + AT2_QS + wave * 8192 + lane * 16;
;         const bf16_t* kg = rest + seq0 * RESTW + R_DK + h * 128; const bf16_t* vg = rest + seq0 * RESTW + R_DV + h * 128;
;         __syncthreads();
;     ...
;         { unsigned dfl = doff0; asm volatile("" : "+v"(dfl)); AT2_DMA(0, 0); }
; #pragma unroll
;         for (int rbq = 0; rbq < 2; ++rbq)
; #pragma unroll
;             for (int d0 = 0; d0 < 4; ++d0) *(LAS bf16x8*)(Qs + (rbq * 4 + d0) * 1024) = qf[rbq][d0];
;         asm volatile("s_waitcnt vmcnt(0)" ::: "memory");
;         __syncthreads();
.LBB0_377:
	s_abs_i32 s1, s58
	s_mul_hi_u32 s8, s1, s55
	s_mul_i32 s9, s8, s53
	s_ashr_i32 s0, s58, 31
	s_sub_i32 s1, s1, s9
	s_xor_b32 s0, s0, s54
	s_add_i32 s9, s8, 1
	s_sub_i32 s10, s1, s53
	s_cmp_ge_u32 s1, s53
	s_cselect_b32 s8, s9, s8
	s_cselect_b32 s1, s10, s1
	s_add_i32 s9, s8, 1
	s_cmp_ge_u32 s1, s53
	s_cselect_b32 s1, s9, s8
	s_xor_b32 s1, s1, s0
	s_sub_i32 s10, s1, s0
	s_mul_i32 s0, s10, s14
	s_sub_i32 s8, s58, s0
	s_ashr_i32 s0, s10, 2
	s_ashr_i32 s1, s0, 31
	v_readlane_b32 s9, v255, 40
	s_lshl_b64 s[0:1], s[0:1], s9
	s_ashr_i32 s9, s8, 31
	s_lshl_b64 s[8:9], s[8:9], 8
	s_add_u32 s40, s0, s8
	s_addc_u32 s41, s1, s9
	v_mov_b32_e32 v2, v245
	s_lshl_b32 s8, s10, 7
	s_and_b32 s59, s8, 0x180
	v_and_or_b32 v0, v2, 31, s13
	s_lshl_b32 s11, s59, 1
	v_ashrrev_i32_e32 v2, 2, v2
	s_add_u32 s8, s16, s11
	v_and_b32_e32 v2, -8, v2
	s_addc_u32 s9, s17, 0
	v_ashrrev_i32_e32 v3, 31, v2
	v_lshl_add_u64 v[2:3], v[2:3], 1, s[8:9]
	s_mulk_i32 s1, 0x1400
	s_mul_hi_u32 s9, s0, 0x1400
	v_or_b32_e32 v0, s40, v0
	v_mov_b32_e32 v1, s41
	s_mul_i32 s30, s0, 0x1400
	s_add_i32 s9, s9, s1
	v_lshlrev_b64 v[0:1], 11, v[0:1]
	s_add_u32 s0, s48, s30
	v_lshl_add_u64 v[16:17], v[2:3], 0, v[0:1]
	s_mov_b32 s8, 0x10000
	s_addc_u32 s1, s49, s9
	v_add_co_u32_e32 v28, vcc, s8, v16
	s_add_u32 s0, s0, s11
	s_nop 0
	v_addc_co_u32_e32 v29, vcc, 0, v17, vcc
	v_mov_b32_e32 v192, v219
	s_addc_u32 s1, s1, 0
	s_mov_b32 m0, s33
	global_load_dwordx4 v[0:3], v[16:17], off
	global_load_dwordx4 v[4:7], v[16:17], off offset:32
	global_load_dwordx4 v[8:11], v[16:17], off offset:64
	global_load_dwordx4 v[12:15], v[16:17], off offset:96
	s_nop 0
	global_load_dwordx4 v[16:19], v[28:29], off
	global_load_dwordx4 v[20:23], v[28:29], off offset:32
	global_load_dwordx4 v[24:27], v[28:29], off offset:64
	s_nop 0
	global_load_dwordx4 v[28:31], v[28:29], off offset:96
	s_barrier
	s_mov_b64 s[84:85], 0x400
	v_lshl_add_u64 v[34:35], s[0:1], 0, v[192:193]
	global_load_lds_dwordx4 v192, s[0:1]
	s_add_i32 m0, s33, 0x4000
	v_lshl_add_u64 v[34:35], v[34:35], 0, s[84:85]
	v_mov_b32_e32 v33, v193
	v_xad_u32 v32, v192, 16, v244
	global_load_lds_dwordx4 v[34:35], off
	s_add_i32 m0, s33, 0x400
	v_lshl_add_u64 v[36:37], s[0:1], 0, v[32:33]
	global_load_lds_dwordx4 v32, s[0:1]
	v_readlane_b32 s0, v254, 37
	v_lshl_add_u64 v[34:35], v[36:37], 0, s[84:85]
	s_mov_b32 m0, s0
	s_and_b32 s10, s10, 3
	global_load_lds_dwordx4 v[34:35], off
	s_lshl_b32 s10, s10, 8
	s_or_b32 s10, s30, s10
	v_mov_b32_e32 v64, 0
	s_add_u32 s30, s56, s10
	s_mov_b32 s8, 0
	v_mov_b32_e32 v222, v221
	s_mov_b32 s38, 0
	v_mov_b32_e32 v65, v64
	v_mov_b32_e32 v66, v64
	s_addc_u32 s31, s57, s9
	v_mov_b32_e32 v67, v64
	v_mov_b32_e32 v68, v64
	v_mov_b32_e32 v69, v64
	v_mov_b32_e32 v70, v64
	v_mov_b32_e32 v71, v64
	v_mov_b32_e32 v72, v64
	v_mov_b32_e32 v73, v64
	v_mov_b32_e32 v74, v64
	v_mov_b32_e32 v75, v64
	v_mov_b32_e32 v76, v64
	v_mov_b32_e32 v77, v64
	v_mov_b32_e32 v78, v64
	v_mov_b32_e32 v79, v64
	v_mov_b32_e32 v80, v64
	s_waitcnt vmcnt(0)
	ds_write_b128 v221, v[0:3]
	ds_write_b128 v221, v[4:7] offset:1024
	ds_write_b128 v221, v[8:11] offset:2048
	ds_write_b128 v221, v[12:15] offset:3072
	ds_write_b128 v221, v[16:19] offset:4096
	ds_write_b128 v221, v[20:23] offset:5120
	ds_write_b128 v221, v[24:27] offset:6144
	ds_write_b128 v221, v[28:31] offset:7168
	s_waitcnt vmcnt(0)
	v_mov_b32_e32 v81, v64
	v_mov_b32_e32 v82, v64
	v_mov_b32_e32 v83, v64
	v_mov_b32_e32 v84, v64
	v_mov_b32_e32 v85, v64
	v_mov_b32_e32 v86, v64
	v_mov_b32_e32 v87, v64
	v_mov_b32_e32 v88, v64
	v_mov_b32_e32 v89, v64
	v_mov_b32_e32 v90, v64
	v_mov_b32_e32 v91, v64
	v_mov_b32_e32 v92, v64
	v_mov_b32_e32 v93, v64
	v_mov_b32_e32 v94, v64
	v_mov_b32_e32 v95, v64
	v_mov_b32_e32 v96, v64
	v_mov_b32_e32 v97, v64
	v_mov_b32_e32 v98, v64
	v_mov_b32_e32 v99, v64
	v_mov_b32_e32 v100, v64
	v_mov_b32_e32 v101, v64
	v_mov_b32_e32 v102, v64
	v_mov_b32_e32 v103, v64
	v_mov_b32_e32 v104, v64
	v_mov_b32_e32 v105, v64
	v_mov_b32_e32 v106, v64
	v_mov_b32_e32 v107, v64
	v_mov_b32_e32 v108, v64
	v_mov_b32_e32 v109, v64
	v_mov_b32_e32 v110, v64
	v_mov_b32_e32 v111, v64
	v_mov_b32_e32 v112, v64
	v_mov_b32_e32 v113, v64
	v_mov_b32_e32 v114, v64
	v_mov_b32_e32 v115, v64
	v_mov_b32_e32 v116, v64
	v_mov_b32_e32 v117, v64
	v_mov_b32_e32 v118, v64
	v_mov_b32_e32 v119, v64
	v_mov_b32_e32 v120, v64
	v_mov_b32_e32 v121, v64
	v_mov_b32_e32 v122, v64
	v_mov_b32_e32 v123, v64
	v_mov_b32_e32 v124, v64
	v_mov_b32_e32 v125, v64
	v_mov_b32_e32 v126, v64
	v_mov_b32_e32 v127, v64
	v_mov_b32_e32 v0, v64
	v_mov_b32_e32 v1, v64
	v_mov_b32_e32 v2, v64
	v_mov_b32_e32 v3, v64
	v_mov_b32_e32 v4, v64
	v_mov_b32_e32 v5, v64
	v_mov_b32_e32 v6, v64
	v_mov_b32_e32 v7, v64
	v_mov_b32_e32 v8, v64
	v_mov_b32_e32 v9, v64
	v_mov_b32_e32 v10, v64
	v_mov_b32_e32 v11, v64
	v_mov_b32_e32 v12, v64
	v_mov_b32_e32 v13, v64
	v_mov_b32_e32 v14, v64
	v_mov_b32_e32 v15, v64
	v_mov_b32_e32 v16, v64
	v_mov_b32_e32 v17, v64
	v_mov_b32_e32 v18, v64
	v_mov_b32_e32 v19, v64
	v_mov_b32_e32 v20, v64
	v_mov_b32_e32 v21, v64
	v_mov_b32_e32 v22, v64
	v_mov_b32_e32 v23, v64
	v_mov_b32_e32 v24, v64
	v_mov_b32_e32 v25, v64
	v_mov_b32_e32 v26, v64
	v_mov_b32_e32 v27, v64
	v_mov_b32_e32 v28, v64
	v_mov_b32_e32 v29, v64
	v_mov_b32_e32 v30, v64
	v_mov_b32_e32 v31, v64
	v_mov_b32_e32 v32, v64
	v_mov_b32_e32 v33, v64
	v_mov_b32_e32 v34, v64
	v_mov_b32_e32 v35, v64
	v_mov_b32_e32 v36, v64
	v_mov_b32_e32 v37, v64
	v_mov_b32_e32 v38, v64
	v_mov_b32_e32 v39, v64
	v_mov_b32_e32 v40, v64
	v_mov_b32_e32 v41, v64
	v_mov_b32_e32 v42, v64
	v_mov_b32_e32 v43, v64
	v_mov_b32_e32 v44, v64
	v_mov_b32_e32 v45, v64
	v_mov_b32_e32 v46, v64
	v_mov_b32_e32 v47, v64
	v_mov_b32_e32 v48, v64
	v_mov_b32_e32 v49, v64
	v_mov_b32_e32 v50, v64
	v_mov_b32_e32 v51, v64
	v_mov_b32_e32 v52, v64
	v_mov_b32_e32 v53, v64
	v_mov_b32_e32 v54, v64
	v_mov_b32_e32 v55, v64
	v_mov_b32_e32 v56, v64
	v_mov_b32_e32 v57, v64
	v_mov_b32_e32 v58, v64
	v_mov_b32_e32 v59, v64
	v_mov_b32_e32 v60, v64
	v_mov_b32_e32 v61, v64
	v_mov_b32_e32 v62, v64
	v_mov_b32_e32 v63, v64
	v_mov_b32_e32 v164, v64
	v_mov_b32_e32 v165, v64
	v_xor_b32_e32 v236, 32, v217
	v_xor_b32_e32 v237, 64, v217
	v_xor_b32_e32 v238, 0x60, v217
	v_xor_b32_e32 v239, 32, v218
	v_xor_b32_e32 v240, 64, v218
	v_xor_b32_e32 v241, 0x60, v218
	v_xor_b32_e32 v248, 0x80, v218
	v_xor_b32_e32 v249, 0xa0, v218
	v_xor_b32_e32 v250, 0xc0, v218
	v_xor_b32_e32 v251, 0xe0, v218
	v_xad_u32 v252, v219, 16, v244
	s_waitcnt lgkmcnt(0)
	s_barrier
	ds_read_b128 v[132:135], v222
	ds_read_b128 v[136:139], v222 offset:1024
	ds_read_b128 v[140:143], v222 offset:2048
	ds_read_b128 v[174:177], v222 offset:3072
	ds_read_b128 v[178:181], v222 offset:5120
	ds_read_b128 v[182:185], v222 offset:6144
	ds_read_b128 v[224:227], v222 offset:7168
	s_branch .LBB0_379
; template <bool SHIFT> DI void phase_attn2(const Params& p, const Grp& G, int layer, LAS unsigned char* lds, int tid, int wave, int lane, int vcu, bool dry) {
;     ...
;             {
;                 f32x16 s0, s1; bf16x8 pa00, pa01, pa10, pa11; bf16x8 kfs[4], qfs[4];
;                 CHAIN(s0, 0, 0, true, true); CHAIN(s1, 0, 1, false, true);
.LBB0_378:
	s_waitcnt lgkmcnt(0)
	v_mfma_f32_32x32x16_bf16 v[144:159], v[128:131], v[132:135], 0
	v_mfma_f32_32x32x16_bf16 v[144:159], v[160:163], v[136:139], v[144:159]
	v_mfma_f32_32x32x16_bf16 v[144:159], v[166:169], v[140:143], v[144:159]
	v_mfma_f32_32x32x16_bf16 v[144:159], v[170:173], v[174:177], v[144:159]
	ds_read_b128 v[174:177], v222 offset:4096
	s_waitcnt lgkmcnt(0)
	v_mfma_f32_32x32x16_bf16 v[128:143], v[128:131], v[174:177], 0
	v_mfma_f32_32x32x16_bf16 v[128:143], v[160:163], v[178:181], v[128:143]
	v_mfma_f32_32x32x16_bf16 v[128:143], v[166:169], v[182:185], v[128:143]
	v_mfma_f32_32x32x16_bf16 v[128:143], v[170:173], v[224:227], v[128:143]
	ds_read_b128 v[170:173], v236 offset:8192
	ds_read_b128 v[228:231], v237 offset:8192
	ds_read_b128 v[232:235], v238 offset:8192
	v_exp_f32_e32 v144, v144
	v_exp_f32_e32 v145, v145
	v_exp_f32_e32 v146, v146
	v_exp_f32_e32 v147, v147
	v_exp_f32_e32 v148, v148
	v_exp_f32_e32 v149, v149
	v_exp_f32_e32 v150, v150
	v_exp_f32_e32 v188, v151
	v_exp_f32_e32 v208, v152
	v_exp_f32_e32 v206, v153
	v_exp_f32_e32 v204, v154
	v_exp_f32_e32 v202, v155
	v_exp_f32_e32 v200, v156
	v_exp_f32_e32 v198, v157
	v_exp_f32_e32 v196, v158
	v_exp_f32_e32 v190, v159
	v_exp_f32_e32 v189, v135
	v_add_f32_e32 v135, v145, v144
	v_exp_f32_e32 v128, v128
	v_exp_f32_e32 v129, v129
	v_exp_f32_e32 v130, v130
	v_exp_f32_e32 v131, v131
	v_exp_f32_e32 v132, v132
	v_exp_f32_e32 v133, v133
	v_exp_f32_e32 v134, v134
	v_add_f32_e32 v135, v146, v135
	v_add_f32_e32 v135, v147, v135
	v_add_f32_e32 v135, v148, v135
	v_add_f32_e32 v135, v149, v135
	v_cvt_pk_bf16_f32 v160, v144, v145
	v_cvt_pk_bf16_f32 v161, v146, v147
	v_cvt_pk_bf16_f32 v162, v148, v149
	v_cvt_pk_bf16_f32 v163, v150, v188
	v_exp_f32_e32 v209, v136
	v_exp_f32_e32 v207, v137
	v_exp_f32_e32 v205, v138
	v_exp_f32_e32 v203, v139
	v_exp_f32_e32 v201, v140
	v_exp_f32_e32 v199, v141
	v_exp_f32_e32 v197, v142
	v_exp_f32_e32 v191, v143
	v_add_f32_e32 v210, v150, v135
	v_cvt_pk_bf16_f32 v166, v128, v129
	v_cvt_pk_bf16_f32 v167, v130, v131
	v_cvt_pk_bf16_f32 v168, v132, v133
	v_cvt_pk_bf16_f32 v169, v134, v189
	ds_read_b128 v[144:147], v217 offset:8192
	v_add_f32_e32 v128, v129, v128
	v_add_f32_e32 v128, v130, v128
	v_add_f32_e32 v128, v131, v128
	v_add_f32_e32 v128, v132, v128
	v_add_f32_e32 v128, v133, v128
	v_add_f32_e32 v211, v134, v128
	s_waitcnt lgkmcnt(0)
	v_mfma_f32_32x32x16_bf16 v[128:143], v[144:147], v[174:177], 0
	v_mfma_f32_32x32x16_bf16 v[128:143], v[170:173], v[178:181], v[128:143]
	v_mfma_f32_32x32x16_bf16 v[128:143], v[228:231], v[182:185], v[128:143]
	v_mfma_f32_32x32x16_bf16 v[128:143], v[232:235], v[224:227], v[128:143]
	ds_read_b128 v[148:151], v222
	ds_read_b128 v[174:177], v222 offset:1024
	ds_read_b128 v[178:181], v222 offset:2048
	ds_read_b128 v[182:185], v222 offset:3072
	s_waitcnt lgkmcnt(0)
	v_mfma_f32_32x32x16_bf16 v[144:159], v[144:147], v[148:151], 0
	v_mfma_f32_32x32x16_bf16 v[144:159], v[170:173], v[174:177], v[144:159]
	v_mfma_f32_32x32x16_bf16 v[144:159], v[228:231], v[178:181], v[144:159]
	v_mfma_f32_32x32x16_bf16 v[144:159], v[232:235], v[182:185], v[144:159]
	s_nop 4
	ds_read_b64_tr_b16 v[170:171], v218 offset:16384
	ds_read_b64_tr_b16 v[172:173], v239 offset:18432
	ds_read_b64_tr_b16 v[174:175], v240 offset:16384
	ds_read_b64_tr_b16 v[176:177], v241 offset:18432
	ds_read_b64_tr_b16 v[178:179], v248 offset:16384
	ds_read_b64_tr_b16 v[180:181], v249 offset:18432
	ds_read_b64_tr_b16 v[182:183], v250 offset:16384
	ds_read_b64_tr_b16 v[184:185], v251 offset:18432
	v_exp_f32_e32 v144, v144
	s_waitcnt lgkmcnt(6)
	v_mfma_f32_32x32x16_bf16 v[112:127], v[160:163], v[170:173], v[112:127]
	v_exp_f32_e32 v145, v145
	v_exp_f32_e32 v146, v146
	v_exp_f32_e32 v147, v147
	v_exp_f32_e32 v148, v148
	v_exp_f32_e32 v149, v149
	v_mfma_f32_32x32x16_bf16 v[0:15], v[166:169], v[170:173], v[0:15]
	v_exp_f32_e32 v170, v151
	v_exp_f32_e32 v172, v154
	s_waitcnt lgkmcnt(4)
	v_mfma_f32_32x32x16_bf16 v[96:111], v[160:163], v[174:177], v[96:111]
	v_mfma_f32_32x32x16_bf16 v[16:31], v[166:169], v[174:177], v[16:31]
	v_exp_f32_e32 v174, v153
	v_exp_f32_e32 v176, v156
	s_waitcnt lgkmcnt(2)
	v_mfma_f32_32x32x16_bf16 v[80:95], v[160:163], v[178:181], v[80:95]
	v_mfma_f32_32x32x16_bf16 v[32:47], v[166:169], v[178:181], v[32:47]
	v_exp_f32_e32 v178, v155
	v_exp_f32_e32 v180, v158
	s_waitcnt lgkmcnt(0)
	v_mfma_f32_32x32x16_bf16 v[64:79], v[160:163], v[182:185], v[64:79]
	v_add_f32_e32 v160, v145, v144
	v_add_f32_e32 v160, v146, v160
	v_add_f32_e32 v160, v147, v160
	v_add_f32_e32 v160, v148, v160
	v_add_f32_e32 v186, v149, v160
	v_cvt_pk_bf16_f32 v144, v144, v145
	v_mfma_f32_32x32x16_bf16 v[48:63], v[166:169], v[182:185], v[48:63]
	v_exp_f32_e32 v166, v150
	v_exp_f32_e32 v168, v152
	v_exp_f32_e32 v182, v157
	v_exp_f32_e32 v184, v159
	v_cvt_pk_bf16_f32 v145, v146, v147
	v_cvt_pk_bf16_f32 v146, v148, v149
	s_nop 0
	ds_read_b64_tr_b16 v[160:161], v218 offset:20480
	ds_read_b64_tr_b16 v[162:163], v239 offset:22528
	ds_read_b64_tr_b16 v[156:157], v240 offset:20480
	ds_read_b64_tr_b16 v[158:159], v241 offset:22528
	ds_read_b64_tr_b16 v[152:153], v248 offset:20480
	ds_read_b64_tr_b16 v[154:155], v249 offset:22528
	ds_read_b64_tr_b16 v[148:149], v250 offset:20480
	ds_read_b64_tr_b16 v[150:151], v251 offset:22528
	v_exp_f32_e32 v223, v128
	v_exp_f32_e32 v224, v129
	v_exp_f32_e32 v225, v130
	v_exp_f32_e32 v226, v131
	v_exp_f32_e32 v227, v132
	v_add_f32_e32 v128, v224, v223
	v_exp_f32_e32 v228, v133
	v_exp_f32_e32 v167, v134
	v_exp_f32_e32 v171, v135
	v_cvt_pk_bf16_f32 v132, v208, v206
	v_cvt_pk_bf16_f32 v133, v204, v202
	v_cvt_pk_bf16_f32 v134, v200, v198
	v_cvt_pk_bf16_f32 v135, v196, v190
	v_add_f32_e32 v128, v225, v128
	v_exp_f32_e32 v169, v136
	v_exp_f32_e32 v175, v137
	v_exp_f32_e32 v173, v138
	v_exp_f32_e32 v179, v139
	v_cvt_pk_bf16_f32 v136, v209, v207
	v_cvt_pk_bf16_f32 v137, v205, v203
	v_cvt_pk_bf16_f32 v138, v201, v199
	v_cvt_pk_bf16_f32 v139, v197, v191
	v_add_f32_e32 v128, v226, v128
	v_add_f32_e32 v128, v227, v128
	v_add_f32_e32 v187, v228, v128
	v_pk_add_f32 v[128:129], v[188:189], v[210:211]
	s_waitcnt lgkmcnt(6)
; #define LAS __attribute__((address_space(3)))
; #define SB() __builtin_amdgcn_sched_barrier(0)
; #define BLOAD(B_, ks_) do { asm volatile("" : "+v"(v0l)); _Pragma("unroll") for (int cb = 0; cb < 4; ++cb) B_[cb] = BFRAG(ks_, cb); SB(); } while (0)
; #define PVMMA(B_, pA_, pB_) do { _Pragma("unroll") for (int cb = 0; cb < 4; ++cb) { o[0][cb] = MFMA32(pA_, B_[cb], o[0][cb]); o[1][cb] = MFMA32(pB_, B_[cb], o[1][cb]); } } while (0)
; template <bool SHIFT> DI void phase_attn2(const Params& p, const Grp& G, int layer, LAS unsigned char* lds, int tid, int wave, int lane, int vcu, bool dry) {
;     ...
;         for (int t = 0; t < NT; ++t) {
;             unsigned dfl = doff0; asm volatile("" : "+v"(dfl));
;             if (t + 1 < NT) AT2_DMA(t + 1, (t + 1) & 1);
;             const LAS unsigned char* Kt = lds + (t & 1) * AT2_BUF; const LAS unsigned char* Vt = Kt + AT2_TILE;
;             int k0l = k0, v0l = v0; asm volatile("" : "+v"(k0l), "+v"(v0l));
;     ...
;                 BLOAD(B, 3);
;                 PVMMA(B, pb01, pb11);
;                 SB();
;             }
;     ...
;             asm volatile("s_waitcnt vmcnt(0)" ::: "memory");
;             __syncthreads();
	v_mfma_f32_32x32x16_bf16 v[112:127], v[132:135], v[160:163], v[112:127]
	v_add_f32_e64 v128, v208, v128
	v_add_f32_e64 v129, v209, v129
	v_exp_f32_e32 v177, v140
	v_pk_add_f32 v[128:129], v[206:207], v[128:129]
	v_exp_f32_e32 v183, v141
	v_pk_add_f32 v[128:129], v[204:205], v[128:129]
	v_exp_f32_e32 v181, v142
	v_pk_add_f32 v[128:129], v[202:203], v[128:129]
	s_waitcnt lgkmcnt(4)
	v_mfma_f32_32x32x16_bf16 v[96:111], v[132:135], v[156:159], v[96:111]
	v_exp_f32_e32 v185, v143
	v_pk_add_f32 v[128:129], v[200:201], v[128:129]
	v_cvt_pk_bf16_f32 v147, v166, v170
	v_pk_add_f32 v[128:129], v[198:199], v[128:129]
	v_cvt_pk_bf16_f32 v130, v176, v182
	v_pk_add_f32 v[128:129], v[196:197], v[128:129]
	v_cvt_pk_bf16_f32 v131, v180, v184
	s_waitcnt lgkmcnt(2)
	v_mfma_f32_32x32x16_bf16 v[80:95], v[132:135], v[152:155], v[80:95]
	v_add_f32_e64 v128, v190, v128
	v_add_f32_e64 v129, v191, v129
	v_add_f32_e64 v140, v164, v128
	v_add_f32_e64 v141, v165, v129
	v_cvt_pk_bf16_f32 v128, v168, v174
	v_cvt_pk_bf16_f32 v129, v172, v178
	s_waitcnt lgkmcnt(0)
	v_mfma_f32_32x32x16_bf16 v[64:79], v[132:135], v[148:151], v[64:79]
	v_add_f32_e64 v132, v166, v186
	v_add_f32_e64 v133, v167, v187
	v_cvt_pk_bf16_f32 v134, v227, v228
	v_add_f32_e64 v132, v170, v132
	v_add_f32_e64 v133, v171, v133
	v_cvt_pk_bf16_f32 v135, v167, v171
	v_pk_add_f32 v[132:133], v[168:169], v[132:133]
	s_nop 0
	v_pk_add_f32 v[132:133], v[174:175], v[132:133]
	v_mfma_f32_32x32x16_bf16 v[0:15], v[136:139], v[160:163], v[0:15]
	v_add_f32_e64 v132, v172, v132
	v_add_f32_e64 v133, v173, v133
	v_add_f32_e64 v132, v178, v132
	v_add_f32_e64 v133, v179, v133
	v_add_f32_e64 v132, v176, v132
	v_add_f32_e64 v133, v177, v133
	v_pk_add_f32 v[132:133], v[182:183], v[132:133]
	v_mfma_f32_32x32x16_bf16 v[16:31], v[136:139], v[156:159], v[16:31]
	v_add_f32_e64 v132, v180, v132
	v_add_f32_e64 v133, v181, v133
	v_add_f32_e64 v142, v184, v132
	v_add_f32_e64 v143, v185, v133
	v_cvt_pk_bf16_f32 v132, v223, v224
	v_cvt_pk_bf16_f32 v133, v225, v226
	v_mfma_f32_32x32x16_bf16 v[32:47], v[136:139], v[152:155], v[32:47]
	v_mfma_f32_32x32x16_bf16 v[48:63], v[136:139], v[148:151], v[48:63]
	v_cvt_pk_bf16_f32 v136, v169, v175
	v_cvt_pk_bf16_f32 v137, v173, v179
	v_cvt_pk_bf16_f32 v138, v177, v183
	v_cvt_pk_bf16_f32 v139, v181, v185
	s_nop 0
	ds_read_b64_tr_b16 v[148:149], v218 offset:24576
	ds_read_b64_tr_b16 v[150:151], v239 offset:26624
	ds_read_b64_tr_b16 v[152:153], v240 offset:24576
	ds_read_b64_tr_b16 v[154:155], v241 offset:26624
	ds_read_b64_tr_b16 v[156:157], v248 offset:24576
	ds_read_b64_tr_b16 v[158:159], v249 offset:26624
	ds_read_b64_tr_b16 v[160:161], v250 offset:24576
	ds_read_b64_tr_b16 v[162:163], v251 offset:26624
	s_waitcnt lgkmcnt(6)
	v_mfma_f32_32x32x16_bf16 v[112:127], v[144:147], v[148:151], v[112:127]
	v_add_f32_e64 v164, v140, v142
	v_add_f32_e64 v165, v141, v143
	v_mfma_f32_32x32x16_bf16 v[0:15], v[132:135], v[148:151], v[0:15]
	s_waitcnt lgkmcnt(4)
	v_mfma_f32_32x32x16_bf16 v[96:111], v[144:147], v[152:155], v[96:111]
	v_mfma_f32_32x32x16_bf16 v[16:31], v[132:135], v[152:155], v[16:31]
	s_waitcnt lgkmcnt(2)
	v_mfma_f32_32x32x16_bf16 v[80:95], v[144:147], v[156:159], v[80:95]
	v_mfma_f32_32x32x16_bf16 v[32:47], v[132:135], v[156:159], v[32:47]
	s_waitcnt lgkmcnt(0)
	v_mfma_f32_32x32x16_bf16 v[64:79], v[144:147], v[160:163], v[64:79]
	v_mfma_f32_32x32x16_bf16 v[48:63], v[132:135], v[160:163], v[48:63]
	s_nop 0
	ds_read_b64_tr_b16 v[132:133], v218 offset:28672
	ds_read_b64_tr_b16 v[134:135], v239 offset:30720
	ds_read_b64_tr_b16 v[140:141], v240 offset:28672
	ds_read_b64_tr_b16 v[142:143], v241 offset:30720
	ds_read_b64_tr_b16 v[144:145], v248 offset:28672
	ds_read_b64_tr_b16 v[146:147], v249 offset:30720
	ds_read_b64_tr_b16 v[148:149], v250 offset:28672
	ds_read_b64_tr_b16 v[150:151], v251 offset:30720
	s_waitcnt lgkmcnt(6)
	v_mfma_f32_32x32x16_bf16 v[112:127], v[128:131], v[132:135], v[112:127]
	v_mfma_f32_32x32x16_bf16 v[0:15], v[136:139], v[132:135], v[0:15]
	ds_read_b128 v[132:135], v222
	ds_read_b128 v[174:177], v222 offset:3072
	s_waitcnt lgkmcnt(6)
	v_mfma_f32_32x32x16_bf16 v[96:111], v[128:131], v[140:143], v[96:111]
	v_mfma_f32_32x32x16_bf16 v[16:31], v[136:139], v[140:143], v[16:31]
	ds_read_b128 v[140:143], v222 offset:2048
	s_waitcnt lgkmcnt(5)
	v_mfma_f32_32x32x16_bf16 v[80:95], v[128:131], v[144:147], v[80:95]
	v_mfma_f32_32x32x16_bf16 v[32:47], v[136:139], v[144:147], v[32:47]
	s_waitcnt lgkmcnt(3)
	v_mfma_f32_32x32x16_bf16 v[64:79], v[128:131], v[148:151], v[64:79]
	v_mfma_f32_32x32x16_bf16 v[48:63], v[136:139], v[148:151], v[48:63]
	ds_read_b128 v[136:139], v222 offset:1024
	ds_read_b128 v[178:181], v222 offset:5120
	ds_read_b128 v[182:185], v222 offset:6144
	ds_read_b128 v[224:227], v222 offset:7168
	s_waitcnt vmcnt(0)
	s_add_u32 s30, s30, 0x50000
	s_addc_u32 s31, s31, 0
	s_cmp_eq_u32 s45, s38
	s_mov_b32 s8, s39
	s_barrier
	s_cbranch_scc1 .LBB0_383
	s_branch .Lat2_top_O

; template <bool SHIFT> DI void phase_attn2(const Params& p, const Grp& G, int layer, LAS unsigned char* lds, int tid, int wave, int lane, int vcu, bool dry) {
;     ...
;             {
;                 f32x16 s0, s1; bf16x8 pa00, pa01, pa10, pa11; bf16x8 kfs[4], qfs[4];
;                 CHAIN(s0, 0, 0, true, true); CHAIN(s1, 0, 1, false, true);
.Lat2_body_O:
	s_waitcnt lgkmcnt(0)
	v_mfma_f32_32x32x16_bf16 v[144:159], v[128:131], v[132:135], 0
	v_mfma_f32_32x32x16_bf16 v[144:159], v[160:163], v[136:139], v[144:159]
	v_mfma_f32_32x32x16_bf16 v[144:159], v[166:169], v[140:143], v[144:159]
	v_mfma_f32_32x32x16_bf16 v[144:159], v[170:173], v[174:177], v[144:159]
	ds_read_b128 v[174:177], v222 offset:4096
	s_waitcnt lgkmcnt(0)
	v_mfma_f32_32x32x16_bf16 v[128:143], v[128:131], v[174:177], 0
	v_mfma_f32_32x32x16_bf16 v[128:143], v[160:163], v[178:181], v[128:143]
	v_mfma_f32_32x32x16_bf16 v[128:143], v[166:169], v[182:185], v[128:143]
	v_mfma_f32_32x32x16_bf16 v[128:143], v[170:173], v[224:227], v[128:143]
	ds_read_b128 v[170:173], v236 offset:40960
	ds_read_b128 v[228:231], v237 offset:40960
	ds_read_b128 v[232:235], v238 offset:40960
	v_exp_f32_e32 v144, v144
	v_exp_f32_e32 v145, v145
	v_exp_f32_e32 v146, v146
	v_exp_f32_e32 v147, v147
	v_exp_f32_e32 v148, v148
	v_exp_f32_e32 v149, v149
	v_exp_f32_e32 v150, v150
	v_exp_f32_e32 v188, v151
	v_exp_f32_e32 v208, v152
	v_exp_f32_e32 v206, v153
	v_exp_f32_e32 v204, v154
	v_exp_f32_e32 v202, v155
	v_exp_f32_e32 v200, v156
	v_exp_f32_e32 v198, v157
	v_exp_f32_e32 v196, v158
	v_exp_f32_e32 v190, v159
	v_exp_f32_e32 v189, v135
	v_add_f32_e32 v135, v145, v144
	v_exp_f32_e32 v128, v128
	v_exp_f32_e32 v129, v129
	v_exp_f32_e32 v130, v130
	v_exp_f32_e32 v131, v131
	v_exp_f32_e32 v132, v132
	v_exp_f32_e32 v133, v133
	v_exp_f32_e32 v134, v134
	v_add_f32_e32 v135, v146, v135
	v_add_f32_e32 v135, v147, v135
	v_add_f32_e32 v135, v148, v135
	v_add_f32_e32 v135, v149, v135
	v_cvt_pk_bf16_f32 v160, v144, v145
	v_cvt_pk_bf16_f32 v161, v146, v147
	v_cvt_pk_bf16_f32 v162, v148, v149
	v_cvt_pk_bf16_f32 v163, v150, v188
	v_exp_f32_e32 v209, v136
	v_exp_f32_e32 v207, v137
	v_exp_f32_e32 v205, v138
	v_exp_f32_e32 v203, v139
	v_exp_f32_e32 v201, v140
	v_exp_f32_e32 v199, v141
	v_exp_f32_e32 v197, v142
	v_exp_f32_e32 v191, v143
	v_add_f32_e32 v210, v150, v135
	v_cvt_pk_bf16_f32 v166, v128, v129
	v_cvt_pk_bf16_f32 v167, v130, v131
	v_cvt_pk_bf16_f32 v168, v132, v133
	v_cvt_pk_bf16_f32 v169, v134, v189
	ds_read_b128 v[144:147], v217 offset:40960
	v_add_f32_e32 v128, v129, v128
	v_add_f32_e32 v128, v130, v128
	v_add_f32_e32 v128, v131, v128
	v_add_f32_e32 v128, v132, v128
	v_add_f32_e32 v128, v133, v128
	v_add_f32_e32 v211, v134, v128
	s_waitcnt lgkmcnt(0)
	v_mfma_f32_32x32x16_bf16 v[128:143], v[144:147], v[174:177], 0
	v_mfma_f32_32x32x16_bf16 v[128:143], v[170:173], v[178:181], v[128:143]
	v_mfma_f32_32x32x16_bf16 v[128:143], v[228:231], v[182:185], v[128:143]
	v_mfma_f32_32x32x16_bf16 v[128:143], v[232:235], v[224:227], v[128:143]
	ds_read_b128 v[148:151], v222
	ds_read_b128 v[174:177], v222 offset:1024
	ds_read_b128 v[178:181], v222 offset:2048
	ds_read_b128 v[182:185], v222 offset:3072
	s_waitcnt lgkmcnt(0)
	v_mfma_f32_32x32x16_bf16 v[144:159], v[144:147], v[148:151], 0
	v_mfma_f32_32x32x16_bf16 v[144:159], v[170:173], v[174:177], v[144:159]
	v_mfma_f32_32x32x16_bf16 v[144:159], v[228:231], v[178:181], v[144:159]
	v_mfma_f32_32x32x16_bf16 v[144:159], v[232:235], v[182:185], v[144:159]
	s_nop 4
	ds_read_b64_tr_b16 v[170:171], v218 offset:49152
	ds_read_b64_tr_b16 v[172:173], v239 offset:51200
	ds_read_b64_tr_b16 v[174:175], v240 offset:49152
	ds_read_b64_tr_b16 v[176:177], v241 offset:51200
	ds_read_b64_tr_b16 v[178:179], v248 offset:49152
	ds_read_b64_tr_b16 v[180:181], v249 offset:51200
	ds_read_b64_tr_b16 v[182:183], v250 offset:49152
	ds_read_b64_tr_b16 v[184:185], v251 offset:51200
	v_exp_f32_e32 v144, v144
	s_waitcnt lgkmcnt(6)
	v_mfma_f32_32x32x16_bf16 v[112:127], v[160:163], v[170:173], v[112:127]
	v_exp_f32_e32 v145, v145
	v_exp_f32_e32 v146, v146
	v_exp_f32_e32 v147, v147
	v_exp_f32_e32 v148, v148
	v_exp_f32_e32 v149, v149
	v_mfma_f32_32x32x16_bf16 v[0:15], v[166:169], v[170:173], v[0:15]
	v_exp_f32_e32 v170, v151
	v_exp_f32_e32 v172, v154
	s_waitcnt lgkmcnt(4)
	v_mfma_f32_32x32x16_bf16 v[96:111], v[160:163], v[174:177], v[96:111]
	v_mfma_f32_32x32x16_bf16 v[16:31], v[166:169], v[174:177], v[16:31]
	v_exp_f32_e32 v174, v153
	v_exp_f32_e32 v176, v156
	s_waitcnt lgkmcnt(2)
	v_mfma_f32_32x32x16_bf16 v[80:95], v[160:163], v[178:181], v[80:95]
	v_mfma_f32_32x32x16_bf16 v[32:47], v[166:169], v[178:181], v[32:47]
	v_exp_f32_e32 v178, v155
	v_exp_f32_e32 v180, v158
	s_waitcnt lgkmcnt(0)
	v_mfma_f32_32x32x16_bf16 v[64:79], v[160:163], v[182:185], v[64:79]
	v_add_f32_e32 v160, v145, v144
	v_add_f32_e32 v160, v146, v160
	v_add_f32_e32 v160, v147, v160
	v_add_f32_e32 v160, v148, v160
	v_add_f32_e32 v186, v149, v160
	v_cvt_pk_bf16_f32 v144, v144, v145
	v_mfma_f32_32x32x16_bf16 v[48:63], v[166:169], v[182:185], v[48:63]
	v_exp_f32_e32 v166, v150
	v_exp_f32_e32 v168, v152
	v_exp_f32_e32 v182, v157
	v_exp_f32_e32 v184, v159
	v_cvt_pk_bf16_f32 v145, v146, v147
	v_cvt_pk_bf16_f32 v146, v148, v149
	s_nop 0
	ds_read_b64_tr_b16 v[160:161], v218 offset:53248
	ds_read_b64_tr_b16 v[162:163], v239 offset:55296
	ds_read_b64_tr_b16 v[156:157], v240 offset:53248
	ds_read_b64_tr_b16 v[158:159], v241 offset:55296
	ds_read_b64_tr_b16 v[152:153], v248 offset:53248
	ds_read_b64_tr_b16 v[154:155], v249 offset:55296
	ds_read_b64_tr_b16 v[148:149], v250 offset:53248
	ds_read_b64_tr_b16 v[150:151], v251 offset:55296
	v_exp_f32_e32 v223, v128
	v_exp_f32_e32 v224, v129
	v_exp_f32_e32 v225, v130
	v_exp_f32_e32 v226, v131
	v_exp_f32_e32 v227, v132
	v_add_f32_e32 v128, v224, v223
	v_exp_f32_e32 v228, v133
	v_exp_f32_e32 v167, v134
	v_exp_f32_e32 v171, v135
	v_cvt_pk_bf16_f32 v132, v208, v206
	v_cvt_pk_bf16_f32 v133, v204, v202
	v_cvt_pk_bf16_f32 v134, v200, v198
	v_cvt_pk_bf16_f32 v135, v196, v190
	v_add_f32_e32 v128, v225, v128
	v_exp_f32_e32 v169, v136
	v_exp_f32_e32 v175, v137
	v_exp_f32_e32 v173, v138
	v_exp_f32_e32 v179, v139
	v_cvt_pk_bf16_f32 v136, v209, v207
	v_cvt_pk_bf16_f32 v137, v205, v203
	v_cvt_pk_bf16_f32 v138, v201, v199
	v_cvt_pk_bf16_f32 v139, v197, v191
	v_add_f32_e32 v128, v226, v128
	v_add_f32_e32 v128, v227, v128
	v_add_f32_e32 v187, v228, v128
	v_pk_add_f32 v[128:129], v[188:189], v[210:211]
	s_waitcnt lgkmcnt(6)
; #define LAS __attribute__((address_space(3)))
; #define SB() __builtin_amdgcn_sched_barrier(0)
; #define BLOAD(B_, ks_) do { asm volatile("" : "+v"(v0l)); _Pragma("unroll") for (int cb = 0; cb < 4; ++cb) B_[cb] = BFRAG(ks_, cb); SB(); } while (0)
; #define PVMMA(B_, pA_, pB_) do { _Pragma("unroll") for (int cb = 0; cb < 4; ++cb) { o[0][cb] = MFMA32(pA_, B_[cb], o[0][cb]); o[1][cb] = MFMA32(pB_, B_[cb], o[1][cb]); } } while (0)
; template <bool SHIFT> DI void phase_attn2(const Params& p, const Grp& G, int layer, LAS unsigned char* lds, int tid, int wave, int lane, int vcu, bool dry) {
;     ...
;         for (int t = 0; t < NT; ++t) {
;             unsigned dfl = doff0; asm volatile("" : "+v"(dfl));
;             if (t + 1 < NT) AT2_DMA(t + 1, (t + 1) & 1);
;             const LAS unsigned char* Kt = lds + (t & 1) * AT2_BUF; const LAS unsigned char* Vt = Kt + AT2_TILE;
;             int k0l = k0, v0l = v0; asm volatile("" : "+v"(k0l), "+v"(v0l));
;     ...
;                 BLOAD(B, 3);
;                 PVMMA(B, pb01, pb11);
;                 SB();
;             }
;     ...
;             asm volatile("s_waitcnt vmcnt(0)" ::: "memory");
;             __syncthreads();
	v_mfma_f32_32x32x16_bf16 v[112:127], v[132:135], v[160:163], v[112:127]
	v_add_f32_e64 v128, v208, v128
	v_add_f32_e64 v129, v209, v129
	v_exp_f32_e32 v177, v140
	v_pk_add_f32 v[128:129], v[206:207], v[128:129]
	v_exp_f32_e32 v183, v141
	v_pk_add_f32 v[128:129], v[204:205], v[128:129]
	v_exp_f32_e32 v181, v142
	v_pk_add_f32 v[128:129], v[202:203], v[128:129]
	s_waitcnt lgkmcnt(4)
	v_mfma_f32_32x32x16_bf16 v[96:111], v[132:135], v[156:159], v[96:111]
	v_exp_f32_e32 v185, v143
	v_pk_add_f32 v[128:129], v[200:201], v[128:129]
	v_cvt_pk_bf16_f32 v147, v166, v170
	v_pk_add_f32 v[128:129], v[198:199], v[128:129]
	v_cvt_pk_bf16_f32 v130, v176, v182
	v_pk_add_f32 v[128:129], v[196:197], v[128:129]
	v_cvt_pk_bf16_f32 v131, v180, v184
	s_waitcnt lgkmcnt(2)
	v_mfma_f32_32x32x16_bf16 v[80:95], v[132:135], v[152:155], v[80:95]
	v_add_f32_e64 v128, v190, v128
	v_add_f32_e64 v129, v191, v129
	v_add_f32_e64 v140, v164, v128
	v_add_f32_e64 v141, v165, v129
	v_cvt_pk_bf16_f32 v128, v168, v174
	v_cvt_pk_bf16_f32 v129, v172, v178
	s_waitcnt lgkmcnt(0)
	v_mfma_f32_32x32x16_bf16 v[64:79], v[132:135], v[148:151], v[64:79]
	v_add_f32_e64 v132, v166, v186
	v_add_f32_e64 v133, v167, v187
	v_cvt_pk_bf16_f32 v134, v227, v228
	v_add_f32_e64 v132, v170, v132
	v_add_f32_e64 v133, v171, v133
	v_cvt_pk_bf16_f32 v135, v167, v171
	v_pk_add_f32 v[132:133], v[168:169], v[132:133]
	s_nop 0
	v_pk_add_f32 v[132:133], v[174:175], v[132:133]
	v_mfma_f32_32x32x16_bf16 v[0:15], v[136:139], v[160:163], v[0:15]
	v_add_f32_e64 v132, v172, v132
	v_add_f32_e64 v133, v173, v133
	v_add_f32_e64 v132, v178, v132
	v_add_f32_e64 v133, v179, v133
	v_add_f32_e64 v132, v176, v132
	v_add_f32_e64 v133, v177, v133
	v_pk_add_f32 v[132:133], v[182:183], v[132:133]
	v_mfma_f32_32x32x16_bf16 v[16:31], v[136:139], v[156:159], v[16:31]
	v_add_f32_e64 v132, v180, v132
	v_add_f32_e64 v133, v181, v133
	v_add_f32_e64 v142, v184, v132
	v_add_f32_e64 v143, v185, v133
	v_cvt_pk_bf16_f32 v132, v223, v224
	v_cvt_pk_bf16_f32 v133, v225, v226
	v_mfma_f32_32x32x16_bf16 v[32:47], v[136:139], v[152:155], v[32:47]
	v_mfma_f32_32x32x16_bf16 v[48:63], v[136:139], v[148:151], v[48:63]
	v_cvt_pk_bf16_f32 v136, v169, v175
	v_cvt_pk_bf16_f32 v137, v173, v179
	v_cvt_pk_bf16_f32 v138, v177, v183
	v_cvt_pk_bf16_f32 v139, v181, v185
	s_nop 0
	ds_read_b64_tr_b16 v[148:149], v218 offset:57344
	ds_read_b64_tr_b16 v[150:151], v239 offset:59392
	ds_read_b64_tr_b16 v[152:153], v240 offset:57344
	ds_read_b64_tr_b16 v[154:155], v241 offset:59392
	ds_read_b64_tr_b16 v[156:157], v248 offset:57344
	ds_read_b64_tr_b16 v[158:159], v249 offset:59392
	ds_read_b64_tr_b16 v[160:161], v250 offset:57344
	ds_read_b64_tr_b16 v[162:163], v251 offset:59392
	s_waitcnt lgkmcnt(6)
	v_mfma_f32_32x32x16_bf16 v[112:127], v[144:147], v[148:151], v[112:127]
	v_add_f32_e64 v164, v140, v142
	v_add_f32_e64 v165, v141, v143
	v_mfma_f32_32x32x16_bf16 v[0:15], v[132:135], v[148:151], v[0:15]
	s_waitcnt lgkmcnt(4)
	v_mfma_f32_32x32x16_bf16 v[96:111], v[144:147], v[152:155], v[96:111]
	v_mfma_f32_32x32x16_bf16 v[16:31], v[132:135], v[152:155], v[16:31]
	s_waitcnt lgkmcnt(2)
	v_mfma_f32_32x32x16_bf16 v[80:95], v[144:147], v[156:159], v[80:95]
	v_mfma_f32_32x32x16_bf16 v[32:47], v[132:135], v[156:159], v[32:47]
	s_waitcnt lgkmcnt(0)
	v_mfma_f32_32x32x16_bf16 v[64:79], v[144:147], v[160:163], v[64:79]
	v_mfma_f32_32x32x16_bf16 v[48:63], v[132:135], v[160:163], v[48:63]
	s_nop 0
	ds_read_b64_tr_b16 v[132:133], v218 offset:61440
	ds_read_b64_tr_b16 v[134:135], v239 offset:63488
	ds_read_b64_tr_b16 v[140:141], v240 offset:61440
	ds_read_b64_tr_b16 v[142:143], v241 offset:63488
	ds_read_b64_tr_b16 v[144:145], v248 offset:61440
	ds_read_b64_tr_b16 v[146:147], v249 offset:63488
	ds_read_b64_tr_b16 v[148:149], v250 offset:61440
	ds_read_b64_tr_b16 v[150:151], v251 offset:63488
	s_waitcnt lgkmcnt(6)
	v_mfma_f32_32x32x16_bf16 v[112:127], v[128:131], v[132:135], v[112:127]
	v_mfma_f32_32x32x16_bf16 v[0:15], v[136:139], v[132:135], v[0:15]
	ds_read_b128 v[132:135], v222
	ds_read_b128 v[174:177], v222 offset:3072
	s_waitcnt lgkmcnt(6)
	v_mfma_f32_32x32x16_bf16 v[96:111], v[128:131], v[140:143], v[96:111]
	v_mfma_f32_32x32x16_bf16 v[16:31], v[136:139], v[140:143], v[16:31]
	ds_read_b128 v[140:143], v222 offset:2048
	s_waitcnt lgkmcnt(5)
	v_mfma_f32_32x32x16_bf16 v[80:95], v[128:131], v[144:147], v[80:95]
	v_mfma_f32_32x32x16_bf16 v[32:47], v[136:139], v[144:147], v[32:47]
	s_waitcnt lgkmcnt(3)
	v_mfma_f32_32x32x16_bf16 v[64:79], v[128:131], v[148:151], v[64:79]
	v_mfma_f32_32x32x16_bf16 v[48:63], v[136:139], v[148:151], v[48:63]
	ds_read_b128 v[136:139], v222 offset:1024
	ds_read_b128 v[178:181], v222 offset:5120
	ds_read_b128 v[182:185], v222 offset:6144
	ds_read_b128 v[224:227], v222 offset:7168
	s_waitcnt vmcnt(0)
	s_add_u32 s30, s30, 0x50000
	s_addc_u32 s31, s31, 0
	s_cmp_eq_u32 s45, s38
	s_mov_b32 s8, s39
	s_barrier
	s_cbranch_scc1 .LBB0_383
	s_branch .LBB0_379
